# lane shuffles that went through LDS (ds_bpermute) replaced by DPP / permlane swaps: MLA phase 16-lane reductions + rope partner exchange, P0 rms-norm full-wave reduction
# baseline (speedup 1.0000x reference)
; __device__ __forceinline__ unsigned pk2(float lo, float hi) { unsigned r; asm volatile("v_cvt_pk_bf16_f32 %0, %1, %2" : "=v"(r) : "v"(lo), "v"(hi)); return r; }
; __device__ __forceinline__ void p0_phase(const float* xin, const float* gain, bf16_t* xb) {
;     ...
;     for (int row = gw; row < TT; row += nw) {
;         const float* xr = xin + (size_t)row * DM; f32x4 v[4]; float ss = 0.f;
; #pragma unroll
;         for (int i = 0; i < 4; ++i) { v[i] = *(const f32x4*)(xr + i * 256 + lane * 4); ss += v[i][0] * v[i][0] + v[i][1] * v[i][1] + v[i][2] * v[i][2] + v[i][3] * v[i][3]; }
; #pragma unroll
;         for (int o = 1; o < 64; o <<= 1) ss += __shfl_xor(ss, o);
;         const float rs = rsqrtf(ss * (1.0f / DM) + 1e-6f);
; #pragma unroll
;         for (int i = 0; i < 4; ++i) { u32x2 w; w.x = pk2(v[i][0] * rs * g[i][0], v[i][1] * rs * g[i][1]); w.y = pk2(v[i][2] * rs * g[i][2], v[i][3] * rs * g[i][3]);
;             *(u32x2*)(xb + (size_t)row * DM + i * 256 + lane * 4) = w; }
;     }
.LBB0_160:
	global_load_dwordx4 v[30:33], v[22:23], off offset:-3072
	global_load_dwordx4 v[34:37], v[22:23], off offset:-2048
	global_load_dwordx4 v[38:41], v[22:23], off offset:-1024
	global_load_dwordx4 v[42:45], v[22:23], off
	v_add_u32_e32 v18, s25, v18
	v_cmp_lt_i32_e32 vcc, s97, v18
	s_or_b64 s[28:29], vcc, s[28:29]
	v_lshl_add_u64 v[22:23], v[22:23], 0, s[14:15]
	s_waitcnt vmcnt(3)
	v_mov_b32_e32 v48, v31
	s_waitcnt vmcnt(2)
	v_mov_b32_e32 v49, v35
	v_mov_b32_e32 v46, v30
	v_mov_b32_e32 v47, v34
	s_waitcnt vmcnt(1)
	v_mov_b32_e32 v56, v39
	s_waitcnt vmcnt(0)
	v_mov_b32_e32 v57, v43
	v_pk_mul_f32 v[48:49], v[48:49], v[48:49]
	v_mov_b32_e32 v50, v32
	v_mov_b32_e32 v51, v36
	v_mov_b32_e32 v54, v38
	v_mov_b32_e32 v55, v42
	v_pk_mul_f32 v[56:57], v[56:57], v[56:57]
	v_pk_fma_f32 v[46:47], v[46:47], v[46:47], v[48:49]
	v_mov_b32_e32 v52, v33
	v_mov_b32_e32 v53, v37
	v_mov_b32_e32 v58, v40
	v_mov_b32_e32 v59, v44
	v_pk_fma_f32 v[48:49], v[54:55], v[54:55], v[56:57]
	v_pk_fma_f32 v[46:47], v[50:51], v[50:51], v[46:47]
	v_mov_b32_e32 v60, v41
	v_mov_b32_e32 v61, v45
	v_pk_fma_f32 v[48:49], v[58:59], v[58:59], v[48:49]
	v_pk_fma_f32 v[46:47], v[52:53], v[52:53], v[46:47]
	v_pk_fma_f32 v[48:49], v[60:61], v[60:61], v[48:49]
	v_add_f32_e32 v19, v46, v47
	v_add_f32_e32 v19, v19, v48
	v_add_f32_e32 v19, v19, v49
	s_nop 1
	v_add_f32_dpp v19, v19, v19 quad_perm:[1,0,3,2] row_mask:0xf bank_mask:0xf
	s_nop 1
	v_add_f32_dpp v19, v19, v19 quad_perm:[2,3,0,1] row_mask:0xf bank_mask:0xf
	s_nop 1
	v_add_f32_dpp v19, v19, v19 row_half_mirror row_mask:0xf bank_mask:0xf
	s_nop 1
	v_add_f32_dpp v19, v19, v19 row_mirror row_mask:0xf bank_mask:0xf
	v_mov_b32_e32 v29, v19
	s_nop 1
	v_permlane16_swap_b32_e32 v19, v29
	v_add_f32_e32 v19, v19, v29
	v_mov_b32_e32 v29, v19
	s_nop 1
	v_permlane32_swap_b32_e32 v19, v29
	v_add_f32_e32 v19, v19, v29
	v_fmamk_f32 v19, v19, 0x3a800000, v193
	v_mul_f32_e32 v29, 0x4b800000, v19
	v_cmp_gt_f32_e32 vcc, s68, v19
	s_nop 1
	v_cndmask_b32_e32 v19, v19, v29, vcc
	v_rsq_f32_e32 v19, v19
	s_nop 0
	v_mul_f32_e32 v29, 0x45800000, v19
	v_cndmask_b32_e32 v19, v19, v29, vcc
	v_mul_f32_e32 v29, v30, v19
	v_mul_f32_e32 v30, v31, v19
	v_mul_f32_e32 v31, v32, v19
	v_mul_f32_e32 v32, v33, v19
	v_mul_f32_e32 v30, v3, v30
	v_mul_f32_e32 v31, v4, v31
	v_mul_f32_e32 v33, v34, v19
	v_mul_f32_e32 v34, v35, v19
	v_mul_f32_e32 v35, v36, v19
	v_mul_f32_e32 v36, v37, v19
	v_mul_f32_e32 v29, v2, v29
	v_mul_f32_e32 v32, v5, v32
	v_cvt_pk_bf16_f32 v30, v29, v30
	v_cvt_pk_bf16_f32 v31, v31, v32
	v_mul_f32_e32 v37, v38, v19
	v_mul_f32_e32 v38, v39, v19
	v_mul_f32_e32 v39, v40, v19
	v_mul_f32_e32 v40, v41, v19
	v_mul_f32_e32 v33, v6, v33
	v_mul_f32_e32 v34, v7, v34
	v_mul_f32_e32 v35, v8, v35
	v_mul_f32_e32 v36, v9, v36
	global_store_dwordx2 v[20:21], v[30:31], off
	v_cvt_pk_bf16_f32 v30, v33, v34
	v_cvt_pk_bf16_f32 v31, v35, v36
	v_mul_f32_e32 v41, v42, v19
	v_mul_f32_e32 v42, v43, v19
	v_mul_f32_e32 v43, v44, v19
	v_mul_f32_e32 v19, v45, v19
	v_mul_f32_e32 v37, v10, v37
	v_mul_f32_e32 v38, v11, v38
	v_mul_f32_e32 v39, v12, v39
	v_mul_f32_e32 v40, v13, v40
	global_store_dwordx2 v[20:21], v[30:31], off offset:512
	v_cvt_pk_bf16_f32 v30, v37, v38
	v_cvt_pk_bf16_f32 v31, v39, v40
	v_mul_f32_e32 v41, v14, v41
	v_mul_f32_e32 v42, v15, v42
	v_mul_f32_e32 v43, v16, v43
	v_mul_f32_e32 v19, v17, v19
	global_store_dwordx2 v[20:21], v[30:31], off offset:1024
	v_cvt_pk_bf16_f32 v30, v41, v42
	v_cvt_pk_bf16_f32 v31, v43, v19
	global_store_dwordx2 v[20:21], v[30:31], off offset:1536
	v_lshl_add_u64 v[20:21], v[20:21], 0, s[12:13]
	s_andn2_b64 exec, exec, s[28:29]
	s_cbranch_execnz .LBB0_160

; __device__ __forceinline__ u32x4 pack8(const float (&f)[8]) { u32x4 w; w.x = pk2(f[0], f[1]); w.y = pk2(f[2], f[3]); w.z = pk2(f[4], f[5]); w.w = pk2(f[6], f[7]); return w; }
; __device__ __forceinline__ void mla_phase(const Params& p, const WsMap& wm, const bf16_t* H, bf16_t* QC, bf16_t* KC, const bf16_t* KV, int Tc, int l) {
;     ...
;         for (int part = 0; part < 4; ++part) {
;             const int isk = part >> 1, h = (part & 1) * 4 + hl;
;             float f[8]; unpack8(w[part], f); float ss = 0.f;
; #pragma unroll
;             for (int i = 0; i < 8; ++i) ss += f[i] * f[i];
;             ss += __shfl_xor(ss, 1); ss += __shfl_xor(ss, 2); ss += __shfl_xor(ss, 4); ss += __shfl_xor(ss, 8);
;             const float rs = rsqrtf(ss * (1.0f / 96.0f) + 1e-6f);
; #pragma unroll
;             for (int i = 0; i < 8; ++i) f[i] = f[i] * rs * (isk ? gk[i] : gq[i]);
; #pragma unroll
;             for (int i = 0; i < 8; ++i) {
;                 const float other = __shfl_xor(f[i], 2);
;                 if (sub >= 8 && sub < 12) f[i] = (sub < 10) ? (f[i] * cc[i] - other * sn[i]) : (f[i] * cc[i] + other * sn[i]);
;             }
;             if (act) { bf16_t* dst = (isk ? KC : QC) + (size_t)row * 768 + h * 96 + sub * 8; *(u32x4*)dst = pack8(f); }
.LBB0_730:
	s_or_b64 exec, exec, s[44:45]
	s_waitcnt lgkmcnt(0)
	v_and_b32_e32 v0, 0x3ffe0, v76
	v_lshlrev_b32_e32 v0, 2, v0
	s_waitcnt vmcnt(0)
	v_lshl_add_u64 v[18:19], v[52:53], 0, v[0:1]
	global_load_dwordx4 v[22:25], v[18:19], off
	global_load_dwordx4 v[14:17], v[18:19], off offset:16
	global_load_dwordx4 v[26:29], v[18:19], off offset:64
	s_nop 0
	global_load_dwordx4 v[18:21], v[18:19], off offset:80
	s_waitcnt vmcnt(4)
	v_lshlrev_b32_e32 v68, 16, v38
	v_and_b32_e32 v69, 0xffff0000, v38
	v_pk_mul_f32 v[70:71], v[68:69], v[68:69]
	v_lshlrev_b32_e32 v78, 16, v39
	v_and_b32_e32 v79, 0xffff0000, v39
	v_pk_mul_f32 v[38:39], v[78:79], v[78:79]
	v_add_f32_e32 v0, v70, v71
	v_lshlrev_b32_e32 v80, 16, v40
	v_and_b32_e32 v81, 0xffff0000, v40
	v_add_f32_e32 v0, v38, v0
	v_pk_mul_f32 v[82:83], v[80:81], v[80:81]
	v_add_f32_e32 v0, v39, v0
	v_lshlrev_b32_e32 v84, 16, v41
	v_and_b32_e32 v85, 0xffff0000, v41
	v_add_f32_e32 v0, v82, v0
	v_pk_mul_f32 v[40:41], v[84:85], v[84:85]
	v_add_f32_e32 v0, v83, v0
	v_add_f32_e32 v0, v40, v0
	v_add_f32_e32 v0, v41, v0
	s_nop 1
	v_add_f32_dpp v0, v0, v0 quad_perm:[1,0,3,2] row_mask:0xf bank_mask:0xf
	s_nop 1
	v_add_f32_dpp v0, v0, v0 quad_perm:[2,3,0,1] row_mask:0xf bank_mask:0xf
	s_nop 1
	v_add_f32_dpp v0, v0, v0 row_half_mirror row_mask:0xf bank_mask:0xf
	s_nop 1
	v_add_f32_dpp v0, v0, v0 row_mirror row_mask:0xf bank_mask:0xf
	s_nop 0
	v_fmamk_f32 v0, v0, 0x3c2aaaab, v193
	v_mul_f32_e32 v38, 0x4b800000, v0
	v_cmp_gt_f32_e32 vcc, s68, v0
	s_nop 1
	v_cndmask_b32_e32 v0, v0, v38, vcc
	v_rsq_f32_e32 v0, v0
	s_nop 0
	v_mul_f32_e32 v38, 0x45800000, v0
	v_cndmask_b32_e32 v0, v0, v38, vcc
	v_pk_mul_f32 v[38:39], v[0:1], v[68:69] op_sel_hi:[0,1]
	v_pk_mul_f32 v[68:69], v[0:1], v[80:81] op_sel_hi:[0,1]
	v_pk_mul_f32 v[40:41], v[0:1], v[78:79] op_sel_hi:[0,1]
	v_pk_mul_f32 v[70:71], v[48:49], v[68:69]
	v_pk_mul_f32 v[68:69], v[0:1], v[84:85] op_sel_hi:[0,1]
	v_pk_mul_f32 v[38:39], v[44:45], v[38:39]
	v_pk_mul_f32 v[40:41], v[46:47], v[40:41]
	v_pk_mul_f32 v[68:69], v[50:51], v[68:69]
	s_nop 1
	v_mov_b32_dpp v82, v38 quad_perm:[2,3,0,1] row_mask:0xf bank_mask:0xf
	v_mov_b32_dpp v81, v39 quad_perm:[2,3,0,1] row_mask:0xf bank_mask:0xf
	v_mov_b32_dpp v80, v40 quad_perm:[2,3,0,1] row_mask:0xf bank_mask:0xf
	v_mov_b32_dpp v79, v41 quad_perm:[2,3,0,1] row_mask:0xf bank_mask:0xf
	v_mov_b32_dpp v78, v70 quad_perm:[2,3,0,1] row_mask:0xf bank_mask:0xf
	v_mov_b32_dpp v77, v71 quad_perm:[2,3,0,1] row_mask:0xf bank_mask:0xf
	v_mov_b32_dpp v43, v68 quad_perm:[2,3,0,1] row_mask:0xf bank_mask:0xf
	v_mov_b32_dpp v0, v69 quad_perm:[2,3,0,1] row_mask:0xf bank_mask:0xf
	s_and_saveexec_b64 s[44:45], s[36:37]
	s_cbranch_execz .LBB0_732
	s_waitcnt vmcnt(1) lgkmcnt(7)
	v_mul_f32_e32 v82, v26, v82
	s_waitcnt lgkmcnt(6)
	v_mul_f32_e32 v81, v27, v81
	s_waitcnt lgkmcnt(5)
	v_mul_f32_e32 v80, v28, v80
	s_waitcnt vmcnt(0) lgkmcnt(3)
	v_mul_f32_e32 v78, v18, v78
	s_waitcnt lgkmcnt(1)
	v_mul_f32_e32 v43, v20, v43
	v_cndmask_b32_e64 v82, v82, -v82, s[42:43]
	v_cndmask_b32_e64 v81, v81, -v81, s[42:43]
	v_cndmask_b32_e64 v80, v80, -v80, s[42:43]
	v_mul_f32_e32 v79, v29, v79
	v_cndmask_b32_e64 v78, v78, -v78, s[42:43]
	v_mul_f32_e32 v77, v19, v77
	v_cndmask_b32_e64 v43, v43, -v43, s[42:43]
	v_fmac_f32_e32 v82, v22, v38
	v_fmac_f32_e32 v81, v23, v39
	v_fmac_f32_e32 v80, v24, v40
	v_cndmask_b32_e64 v79, v79, -v79, s[42:43]
	v_fmac_f32_e32 v78, v14, v70
	v_cndmask_b32_e64 v77, v77, -v77, s[42:43]
	v_fmac_f32_e32 v43, v16, v68
	v_fmac_f32_e32 v79, v25, v41
	v_fmac_f32_e32 v77, v15, v71
	v_cndmask_b32_e64 v43, v68, v43, s[40:41]
	v_cndmask_b32_e64 v78, v70, v78, s[40:41]
	v_cndmask_b32_e64 v80, v40, v80, s[40:41]
	v_cndmask_b32_e64 v81, v39, v81, s[40:41]
	v_cndmask_b32_e64 v82, v38, v82, s[40:41]
	s_waitcnt lgkmcnt(0)
	v_mul_f32_e32 v0, v21, v0
	v_cndmask_b32_e64 v77, v71, v77, s[40:41]
	v_cndmask_b32_e64 v79, v41, v79, s[40:41]
	v_cndmask_b32_e64 v0, v0, -v0, s[42:43]
	v_cndmask_b32_e64 v43, v68, v43, s[40:41]
	v_cndmask_b32_e64 v68, v70, v78, s[40:41]
	v_cndmask_b32_e64 v40, v40, v80, s[40:41]
	v_cndmask_b32_e64 v38, v38, v82, s[40:41]
	v_cndmask_b32_e64 v39, v39, v81, s[40:41]
	v_fmac_f32_e32 v0, v17, v69
	v_cndmask_b32_e64 v70, v71, v77, s[40:41]
	v_cndmask_b32_e64 v41, v41, v79, s[40:41]
	v_cvt_pk_bf16_f32 v38, v38, v39
	v_cvt_pk_bf16_f32 v39, v40, v41
	v_cvt_pk_bf16_f32 v40, v68, v70
	v_add_co_u32_e32 v68, vcc, 0xc8ca000, v66
	v_cndmask_b32_e64 v0, v69, v0, s[40:41]
	s_nop 0
	v_addc_co_u32_e32 v69, vcc, 0, v67, vcc
	v_cvt_pk_bf16_f32 v41, v43, v0
	global_store_dwordx4 v[68:69], v[38:41], off offset:256
; __device__ __forceinline__ u32x4 pack8(const float (&f)[8]) { u32x4 w; w.x = pk2(f[0], f[1]); w.y = pk2(f[2], f[3]); w.z = pk2(f[4], f[5]); w.w = pk2(f[6], f[7]); return w; }
; __device__ __forceinline__ void mla_phase(const Params& p, const WsMap& wm, const bf16_t* H, bf16_t* QC, bf16_t* KC, const bf16_t* KV, int Tc, int l) {
;     ...
;         for (int part = 0; part < 4; ++part) {
;             const int isk = part >> 1, h = (part & 1) * 4 + hl;
;             float f[8]; unpack8(w[part], f); float ss = 0.f;
; #pragma unroll
;             for (int i = 0; i < 8; ++i) ss += f[i] * f[i];
;             ss += __shfl_xor(ss, 1); ss += __shfl_xor(ss, 2); ss += __shfl_xor(ss, 4); ss += __shfl_xor(ss, 8);
;             const float rs = rsqrtf(ss * (1.0f / 96.0f) + 1e-6f);
; #pragma unroll
;             for (int i = 0; i < 8; ++i) f[i] = f[i] * rs * (isk ? gk[i] : gq[i]);
; #pragma unroll
;             for (int i = 0; i < 8; ++i) {
;                 const float other = __shfl_xor(f[i], 2);
;                 if (sub >= 8 && sub < 12) f[i] = (sub < 10) ? (f[i] * cc[i] - other * sn[i]) : (f[i] * cc[i] + other * sn[i]);
;             }
;             if (act) { bf16_t* dst = (isk ? KC : QC) + (size_t)row * 768 + h * 96 + sub * 8; *(u32x4*)dst = pack8(f); }
.LBB0_732:
	s_or_b64 exec, exec, s[44:45]
	s_nop 0
	v_lshlrev_b32_e32 v38, 16, v34
	v_and_b32_e32 v39, 0xffff0000, v34
	v_pk_mul_f32 v[40:41], v[38:39], v[38:39]
	v_lshlrev_b32_e32 v34, 16, v35
	v_and_b32_e32 v35, 0xffff0000, v35
	v_pk_mul_f32 v[68:69], v[34:35], v[34:35]
	s_waitcnt lgkmcnt(0)
	v_add_f32_e32 v0, v40, v41
	v_lshlrev_b32_e32 v70, 16, v36
	v_and_b32_e32 v71, 0xffff0000, v36
	v_add_f32_e32 v0, v68, v0
	v_pk_mul_f32 v[78:79], v[70:71], v[70:71]
	v_add_f32_e32 v0, v69, v0
	v_lshlrev_b32_e32 v36, 16, v37
	v_and_b32_e32 v37, 0xffff0000, v37
	v_add_f32_e32 v0, v78, v0
	v_pk_mul_f32 v[80:81], v[36:37], v[36:37]
	v_add_f32_e32 v0, v79, v0
	v_add_f32_e32 v0, v80, v0
	v_add_f32_e32 v0, v81, v0
	s_nop 1
	v_add_f32_dpp v0, v0, v0 quad_perm:[1,0,3,2] row_mask:0xf bank_mask:0xf
	s_nop 1
	v_add_f32_dpp v0, v0, v0 quad_perm:[2,3,0,1] row_mask:0xf bank_mask:0xf
	s_nop 1
	v_add_f32_dpp v0, v0, v0 row_half_mirror row_mask:0xf bank_mask:0xf
	s_nop 1
	v_add_f32_dpp v0, v0, v0 row_mirror row_mask:0xf bank_mask:0xf
	s_nop 0
	v_fmamk_f32 v0, v0, 0x3c2aaaab, v193
	v_mul_f32_e32 v40, 0x4b800000, v0
	v_cmp_gt_f32_e32 vcc, s68, v0
	s_nop 1
	v_cndmask_b32_e32 v0, v0, v40, vcc
	v_rsq_f32_e32 v0, v0
	s_nop 0
	v_mul_f32_e32 v40, 0x45800000, v0
	v_cndmask_b32_e32 v0, v0, v40, vcc
	v_pk_mul_f32 v[38:39], v[0:1], v[38:39] op_sel_hi:[0,1]
	v_pk_mul_f32 v[40:41], v[0:1], v[34:35] op_sel_hi:[0,1]
	v_pk_mul_f32 v[68:69], v[0:1], v[70:71] op_sel_hi:[0,1]
	v_pk_mul_f32 v[36:37], v[0:1], v[36:37] op_sel_hi:[0,1]
	v_pk_mul_f32 v[34:35], v[44:45], v[38:39]
	v_pk_mul_f32 v[38:39], v[46:47], v[40:41]
	v_pk_mul_f32 v[40:41], v[48:49], v[68:69]
	v_pk_mul_f32 v[36:37], v[50:51], v[36:37]
	s_nop 1
	v_mov_b32_dpp v78, v34 quad_perm:[2,3,0,1] row_mask:0xf bank_mask:0xf
	v_mov_b32_dpp v77, v35 quad_perm:[2,3,0,1] row_mask:0xf bank_mask:0xf
	v_mov_b32_dpp v71, v38 quad_perm:[2,3,0,1] row_mask:0xf bank_mask:0xf
	v_mov_b32_dpp v70, v39 quad_perm:[2,3,0,1] row_mask:0xf bank_mask:0xf
	v_mov_b32_dpp v69, v40 quad_perm:[2,3,0,1] row_mask:0xf bank_mask:0xf
	v_mov_b32_dpp v68, v41 quad_perm:[2,3,0,1] row_mask:0xf bank_mask:0xf
	v_mov_b32_dpp v43, v36 quad_perm:[2,3,0,1] row_mask:0xf bank_mask:0xf
	v_mov_b32_dpp v0, v37 quad_perm:[2,3,0,1] row_mask:0xf bank_mask:0xf
	s_and_saveexec_b64 s[44:45], s[36:37]
	s_cbranch_execz .LBB0_734
	s_waitcnt vmcnt(1) lgkmcnt(7)
	v_mul_f32_e32 v78, v26, v78
	s_waitcnt lgkmcnt(6)
	v_mul_f32_e32 v77, v27, v77
	s_waitcnt lgkmcnt(5)
	v_mul_f32_e32 v71, v28, v71
	v_cndmask_b32_e64 v78, v78, -v78, s[42:43]
	v_cndmask_b32_e64 v77, v77, -v77, s[42:43]
	v_cndmask_b32_e64 v71, v71, -v71, s[42:43]
	s_waitcnt lgkmcnt(4)
	v_mul_f32_e32 v70, v29, v70
	v_fmac_f32_e32 v78, v22, v34
	v_fmac_f32_e32 v77, v23, v35
	v_fmac_f32_e32 v71, v24, v38
	v_cndmask_b32_e64 v70, v70, -v70, s[42:43]
	s_waitcnt vmcnt(0) lgkmcnt(3)
	v_mul_f32_e32 v69, v18, v69
	s_waitcnt lgkmcnt(1)
	v_mul_f32_e32 v43, v20, v43
	v_fmac_f32_e32 v70, v25, v39
	v_cndmask_b32_e64 v69, v69, -v69, s[42:43]
	v_mul_f32_e32 v68, v19, v68
	v_cndmask_b32_e64 v43, v43, -v43, s[42:43]
	v_cndmask_b32_e64 v71, v38, v71, s[40:41]
	v_cndmask_b32_e64 v77, v35, v77, s[40:41]
	v_cndmask_b32_e64 v78, v34, v78, s[40:41]
	v_fmac_f32_e32 v69, v14, v40
	v_cndmask_b32_e64 v68, v68, -v68, s[42:43]
	v_fmac_f32_e32 v43, v16, v36
	v_cndmask_b32_e64 v70, v39, v70, s[40:41]
	s_waitcnt lgkmcnt(0)
	v_mul_f32_e32 v0, v21, v0
	v_cndmask_b32_e64 v38, v38, v71, s[40:41]
	v_cndmask_b32_e64 v34, v34, v78, s[40:41]
	v_cndmask_b32_e64 v35, v35, v77, s[40:41]
	v_fmac_f32_e32 v68, v15, v41
	v_cndmask_b32_e64 v43, v36, v43, s[40:41]
	v_cndmask_b32_e64 v69, v40, v69, s[40:41]
	v_cndmask_b32_e64 v0, v0, -v0, s[42:43]
	v_cndmask_b32_e64 v39, v39, v70, s[40:41]
	v_cvt_pk_bf16_f32 v34, v34, v35
	v_cvt_pk_bf16_f32 v35, v38, v39
	v_add_co_u32_e32 v38, vcc, 0xc8ca000, v66
	v_cndmask_b32_e64 v68, v41, v68, s[40:41]
	v_fmac_f32_e32 v0, v17, v37
	v_cndmask_b32_e64 v43, v36, v43, s[40:41]
	v_cndmask_b32_e64 v36, v40, v69, s[40:41]
	v_addc_co_u32_e32 v39, vcc, 0, v67, vcc
	v_cndmask_b32_e64 v40, v41, v68, s[40:41]
	v_cndmask_b32_e64 v0, v37, v0, s[40:41]
	v_cvt_pk_bf16_f32 v36, v36, v40
	v_cvt_pk_bf16_f32 v37, v43, v0
	global_store_dwordx4 v[38:39], v[34:37], off offset:1024
; __device__ __forceinline__ u32x4 pack8(const float (&f)[8]) { u32x4 w; w.x = pk2(f[0], f[1]); w.y = pk2(f[2], f[3]); w.z = pk2(f[4], f[5]); w.w = pk2(f[6], f[7]); return w; }
; __device__ __forceinline__ void mla_phase(const Params& p, const WsMap& wm, const bf16_t* H, bf16_t* QC, bf16_t* KC, const bf16_t* KV, int Tc, int l) {
;     ...
;         for (int part = 0; part < 4; ++part) {
;             const int isk = part >> 1, h = (part & 1) * 4 + hl;
;             float f[8]; unpack8(w[part], f); float ss = 0.f;
; #pragma unroll
;             for (int i = 0; i < 8; ++i) ss += f[i] * f[i];
;             ss += __shfl_xor(ss, 1); ss += __shfl_xor(ss, 2); ss += __shfl_xor(ss, 4); ss += __shfl_xor(ss, 8);
;             const float rs = rsqrtf(ss * (1.0f / 96.0f) + 1e-6f);
; #pragma unroll
;             for (int i = 0; i < 8; ++i) f[i] = f[i] * rs * (isk ? gk[i] : gq[i]);
; #pragma unroll
;             for (int i = 0; i < 8; ++i) {
;                 const float other = __shfl_xor(f[i], 2);
;                 if (sub >= 8 && sub < 12) f[i] = (sub < 10) ? (f[i] * cc[i] - other * sn[i]) : (f[i] * cc[i] + other * sn[i]);
;             }
;             if (act) { bf16_t* dst = (isk ? KC : QC) + (size_t)row * 768 + h * 96 + sub * 8; *(u32x4*)dst = pack8(f); }
.LBB0_734:
	s_or_b64 exec, exec, s[44:45]
	s_nop 0
	v_lshlrev_b32_e32 v34, 16, v30
	v_and_b32_e32 v35, 0xffff0000, v30
	v_pk_mul_f32 v[36:37], v[34:35], v[34:35]
	v_lshlrev_b32_e32 v30, 16, v31
	v_and_b32_e32 v31, 0xffff0000, v31
	v_pk_mul_f32 v[38:39], v[30:31], v[30:31]
	s_waitcnt lgkmcnt(0)
	v_add_f32_e32 v0, v36, v37
	v_lshlrev_b32_e32 v40, 16, v32
	v_and_b32_e32 v41, 0xffff0000, v32
	v_add_f32_e32 v0, v38, v0
	v_pk_mul_f32 v[66:67], v[40:41], v[40:41]
	v_add_f32_e32 v0, v39, v0
	v_lshlrev_b32_e32 v32, 16, v33
	v_and_b32_e32 v33, 0xffff0000, v33
	v_add_f32_e32 v0, v66, v0
	v_pk_mul_f32 v[68:69], v[32:33], v[32:33]
	v_add_f32_e32 v0, v67, v0
	v_add_f32_e32 v0, v68, v0
	v_add_f32_e32 v0, v69, v0
	s_nop 1
	v_add_f32_dpp v0, v0, v0 quad_perm:[1,0,3,2] row_mask:0xf bank_mask:0xf
	s_nop 1
	v_add_f32_dpp v0, v0, v0 quad_perm:[2,3,0,1] row_mask:0xf bank_mask:0xf
	s_nop 1
	v_add_f32_dpp v0, v0, v0 row_half_mirror row_mask:0xf bank_mask:0xf
	s_nop 1
	v_add_f32_dpp v0, v0, v0 row_mirror row_mask:0xf bank_mask:0xf
	s_nop 0
	v_fmamk_f32 v0, v0, 0x3c2aaaab, v193
	v_mul_f32_e32 v36, 0x4b800000, v0
	v_cmp_gt_f32_e32 vcc, s68, v0
	s_nop 1
	v_cndmask_b32_e32 v0, v0, v36, vcc
	v_rsq_f32_e32 v0, v0
	s_nop 0
	v_mul_f32_e32 v36, 0x45800000, v0
	v_cndmask_b32_e32 v0, v0, v36, vcc
	v_pk_mul_f32 v[34:35], v[0:1], v[34:35] op_sel_hi:[0,1]
	v_pk_mul_f32 v[30:31], v[0:1], v[30:31] op_sel_hi:[0,1]
	v_pk_mul_f32 v[38:39], v[0:1], v[40:41] op_sel_hi:[0,1]
	v_pk_mul_f32 v[40:41], v[0:1], v[32:33] op_sel_hi:[0,1]
	v_pk_mul_f32 v[32:33], v[6:7], v[34:35]
	v_pk_mul_f32 v[36:37], v[8:9], v[30:31]
	v_pk_mul_f32 v[38:39], v[2:3], v[38:39]
	v_pk_mul_f32 v[34:35], v[4:5], v[40:41]
	s_nop 1
	v_mov_b32_dpp v69, v32 quad_perm:[2,3,0,1] row_mask:0xf bank_mask:0xf
	v_mov_b32_dpp v68, v33 quad_perm:[2,3,0,1] row_mask:0xf bank_mask:0xf
	v_mov_b32_dpp v67, v36 quad_perm:[2,3,0,1] row_mask:0xf bank_mask:0xf
	v_mov_b32_dpp v66, v37 quad_perm:[2,3,0,1] row_mask:0xf bank_mask:0xf
	v_mov_b32_dpp v43, v38 quad_perm:[2,3,0,1] row_mask:0xf bank_mask:0xf
	v_mov_b32_dpp v41, v39 quad_perm:[2,3,0,1] row_mask:0xf bank_mask:0xf
	v_mov_b32_dpp v40, v34 quad_perm:[2,3,0,1] row_mask:0xf bank_mask:0xf
	v_mov_b32_dpp v0, v35 quad_perm:[2,3,0,1] row_mask:0xf bank_mask:0xf
	v_lshl_add_u64 v[30:31], v[60:61], 0, v[54:55]
	s_and_saveexec_b64 s[44:45], s[36:37]
	s_cbranch_execz .LBB0_736
	s_waitcnt vmcnt(1) lgkmcnt(7)
	v_mul_f32_e32 v69, v26, v69
	s_waitcnt lgkmcnt(6)
	v_mul_f32_e32 v68, v27, v68
	s_waitcnt lgkmcnt(5)
	v_mul_f32_e32 v67, v28, v67
	v_cndmask_b32_e64 v69, v69, -v69, s[42:43]
	v_cndmask_b32_e64 v68, v68, -v68, s[42:43]
	v_cndmask_b32_e64 v67, v67, -v67, s[42:43]
	s_waitcnt lgkmcnt(4)
	v_mul_f32_e32 v66, v29, v66
	v_fmac_f32_e32 v69, v22, v32
	v_fmac_f32_e32 v68, v23, v33
	v_fmac_f32_e32 v67, v24, v36
	v_cndmask_b32_e64 v66, v66, -v66, s[42:43]
	s_waitcnt vmcnt(0) lgkmcnt(3)
	v_mul_f32_e32 v43, v18, v43
	s_waitcnt lgkmcnt(1)
	v_mul_f32_e32 v40, v20, v40
	v_fmac_f32_e32 v66, v25, v37
	v_cndmask_b32_e64 v43, v43, -v43, s[42:43]
	v_mul_f32_e32 v41, v19, v41
	v_cndmask_b32_e64 v40, v40, -v40, s[42:43]
	v_cndmask_b32_e64 v67, v36, v67, s[40:41]
	v_cndmask_b32_e64 v68, v33, v68, s[40:41]
	v_cndmask_b32_e64 v69, v32, v69, s[40:41]
	v_fmac_f32_e32 v43, v14, v38
	v_cndmask_b32_e64 v41, v41, -v41, s[42:43]
	v_fmac_f32_e32 v40, v16, v34
	v_cndmask_b32_e64 v66, v37, v66, s[40:41]
	s_waitcnt lgkmcnt(0)
	v_mul_f32_e32 v0, v21, v0
	v_cndmask_b32_e64 v36, v36, v67, s[40:41]
	v_cndmask_b32_e64 v32, v32, v69, s[40:41]
	v_cndmask_b32_e64 v33, v33, v68, s[40:41]
	v_fmac_f32_e32 v41, v15, v39
	v_cndmask_b32_e64 v40, v34, v40, s[40:41]
	v_cndmask_b32_e64 v43, v38, v43, s[40:41]
	v_cndmask_b32_e64 v0, v0, -v0, s[42:43]
	v_cndmask_b32_e64 v37, v37, v66, s[40:41]
	v_cvt_pk_bf16_f32 v32, v32, v33
	v_cvt_pk_bf16_f32 v33, v36, v37
	v_add_co_u32_e32 v36, vcc, 0xc8ca000, v30
	v_cndmask_b32_e64 v41, v39, v41, s[40:41]
	v_fmac_f32_e32 v0, v17, v35
	v_cndmask_b32_e64 v40, v34, v40, s[40:41]
	v_cndmask_b32_e64 v34, v38, v43, s[40:41]
	v_addc_co_u32_e32 v37, vcc, 0, v31, vcc
	v_cndmask_b32_e64 v38, v39, v41, s[40:41]
	v_cndmask_b32_e64 v0, v35, v0, s[40:41]
	v_cvt_pk_bf16_f32 v34, v34, v38
	v_cvt_pk_bf16_f32 v35, v40, v0
	global_store_dwordx4 v[36:37], v[32:35], off offset:256
; __device__ __forceinline__ u32x4 pack8(const float (&f)[8]) { u32x4 w; w.x = pk2(f[0], f[1]); w.y = pk2(f[2], f[3]); w.z = pk2(f[4], f[5]); w.w = pk2(f[6], f[7]); return w; }
; __device__ __forceinline__ void mla_phase(const Params& p, const WsMap& wm, const bf16_t* H, bf16_t* QC, bf16_t* KC, const bf16_t* KV, int Tc, int l) {
;     ...
;         for (int part = 0; part < 4; ++part) {
;             const int isk = part >> 1, h = (part & 1) * 4 + hl;
;             float f[8]; unpack8(w[part], f); float ss = 0.f;
; #pragma unroll
;             for (int i = 0; i < 8; ++i) ss += f[i] * f[i];
;             ss += __shfl_xor(ss, 1); ss += __shfl_xor(ss, 2); ss += __shfl_xor(ss, 4); ss += __shfl_xor(ss, 8);
;             const float rs = rsqrtf(ss * (1.0f / 96.0f) + 1e-6f);
; #pragma unroll
;             for (int i = 0; i < 8; ++i) f[i] = f[i] * rs * (isk ? gk[i] : gq[i]);
; #pragma unroll
;             for (int i = 0; i < 8; ++i) {
;                 const float other = __shfl_xor(f[i], 2);
;                 if (sub >= 8 && sub < 12) f[i] = (sub < 10) ? (f[i] * cc[i] - other * sn[i]) : (f[i] * cc[i] + other * sn[i]);
;             }
;             if (act) { bf16_t* dst = (isk ? KC : QC) + (size_t)row * 768 + h * 96 + sub * 8; *(u32x4*)dst = pack8(f); }
.LBB0_736:
	s_or_b64 exec, exec, s[44:45]
	s_nop 0
	v_lshlrev_b32_e32 v32, 16, v10
	v_and_b32_e32 v33, 0xffff0000, v10
	v_pk_mul_f32 v[34:35], v[32:33], v[32:33]
	v_lshlrev_b32_e32 v10, 16, v11
	v_and_b32_e32 v11, 0xffff0000, v11
	v_pk_mul_f32 v[36:37], v[10:11], v[10:11]
	s_waitcnt lgkmcnt(0)
	v_add_f32_e32 v0, v34, v35
	v_lshlrev_b32_e32 v38, 16, v12
	v_and_b32_e32 v39, 0xffff0000, v12
	v_add_f32_e32 v0, v36, v0
	v_pk_mul_f32 v[40:41], v[38:39], v[38:39]
	v_add_f32_e32 v0, v37, v0
	v_lshlrev_b32_e32 v12, 16, v13
	v_and_b32_e32 v13, 0xffff0000, v13
	v_add_f32_e32 v0, v40, v0
	v_pk_mul_f32 v[66:67], v[12:13], v[12:13]
	v_add_f32_e32 v0, v41, v0
	v_add_f32_e32 v0, v66, v0
	v_add_f32_e32 v0, v67, v0
	s_nop 1
	v_add_f32_dpp v0, v0, v0 quad_perm:[1,0,3,2] row_mask:0xf bank_mask:0xf
	s_nop 1
	v_add_f32_dpp v0, v0, v0 quad_perm:[2,3,0,1] row_mask:0xf bank_mask:0xf
	s_nop 1
	v_add_f32_dpp v0, v0, v0 row_half_mirror row_mask:0xf bank_mask:0xf
	s_nop 1
	v_add_f32_dpp v0, v0, v0 row_mirror row_mask:0xf bank_mask:0xf
	s_nop 0
	v_fmamk_f32 v0, v0, 0x3c2aaaab, v193
	v_mul_f32_e32 v34, 0x4b800000, v0
	v_cmp_gt_f32_e32 vcc, s68, v0
	s_nop 1
	v_cndmask_b32_e32 v0, v0, v34, vcc
	v_rsq_f32_e32 v0, v0
	s_nop 0
	v_mul_f32_e32 v34, 0x45800000, v0
	v_cndmask_b32_e32 v0, v0, v34, vcc
	v_pk_mul_f32 v[32:33], v[0:1], v[32:33] op_sel_hi:[0,1]
	v_pk_mul_f32 v[34:35], v[0:1], v[10:11] op_sel_hi:[0,1]
	v_pk_mul_f32 v[36:37], v[0:1], v[38:39] op_sel_hi:[0,1]
	v_pk_mul_f32 v[12:13], v[0:1], v[12:13] op_sel_hi:[0,1]
	v_pk_mul_f32 v[10:11], v[6:7], v[32:33]
	v_pk_mul_f32 v[32:33], v[8:9], v[34:35]
	v_pk_mul_f32 v[34:35], v[2:3], v[36:37]
	v_pk_mul_f32 v[12:13], v[4:5], v[12:13]
	s_nop 1
	v_mov_b32_dpp v43, v10 quad_perm:[2,3,0,1] row_mask:0xf bank_mask:0xf
	v_mov_b32_dpp v41, v11 quad_perm:[2,3,0,1] row_mask:0xf bank_mask:0xf
	v_mov_b32_dpp v40, v32 quad_perm:[2,3,0,1] row_mask:0xf bank_mask:0xf
	v_mov_b32_dpp v39, v33 quad_perm:[2,3,0,1] row_mask:0xf bank_mask:0xf
	v_mov_b32_dpp v38, v34 quad_perm:[2,3,0,1] row_mask:0xf bank_mask:0xf
	v_mov_b32_dpp v37, v35 quad_perm:[2,3,0,1] row_mask:0xf bank_mask:0xf
	v_mov_b32_dpp v36, v12 quad_perm:[2,3,0,1] row_mask:0xf bank_mask:0xf
	v_mov_b32_dpp v0, v13 quad_perm:[2,3,0,1] row_mask:0xf bank_mask:0xf
	s_and_saveexec_b64 s[44:45], s[36:37]
	s_cbranch_execz .LBB0_713
	s_waitcnt vmcnt(1) lgkmcnt(7)
	v_mul_f32_e32 v26, v26, v43
	v_cndmask_b32_e64 v26, v26, -v26, s[42:43]
	s_waitcnt vmcnt(0) lgkmcnt(3)
	v_mul_f32_e32 v18, v18, v38
	v_fmac_f32_e32 v26, v22, v10
	v_mul_f32_e32 v22, v27, v41
	v_cndmask_b32_e64 v18, v18, -v18, s[42:43]
	v_cndmask_b32_e64 v22, v22, -v22, s[42:43]
	v_fmac_f32_e32 v18, v14, v34
	s_waitcnt lgkmcnt(2)
	v_mul_f32_e32 v14, v19, v37
	v_fmac_f32_e32 v22, v23, v11
	v_mul_f32_e32 v23, v28, v40
	v_cndmask_b32_e64 v14, v14, -v14, s[42:43]
	v_cndmask_b32_e64 v23, v23, -v23, s[42:43]
	v_fmac_f32_e32 v14, v15, v35
	s_waitcnt lgkmcnt(1)
	v_mul_f32_e32 v15, v20, v36
	v_fmac_f32_e32 v23, v24, v32
	v_mul_f32_e32 v24, v29, v39
	v_cndmask_b32_e64 v15, v15, -v15, s[42:43]
	v_cndmask_b32_e64 v24, v24, -v24, s[42:43]
	v_fmac_f32_e32 v15, v16, v12
	v_fmac_f32_e32 v24, v25, v33
	v_cndmask_b32_e64 v15, v12, v15, s[40:41]
	v_cndmask_b32_e64 v14, v35, v14, s[40:41]
	v_cndmask_b32_e64 v16, v34, v18, s[40:41]
	v_cndmask_b32_e64 v20, v11, v22, s[40:41]
	v_cndmask_b32_e64 v22, v10, v26, s[40:41]
	s_waitcnt lgkmcnt(0)
	v_mul_f32_e32 v0, v21, v0
	v_cndmask_b32_e64 v18, v33, v24, s[40:41]
	v_cndmask_b32_e64 v19, v32, v23, s[40:41]
	v_cndmask_b32_e64 v0, v0, -v0, s[42:43]
	v_cndmask_b32_e64 v15, v12, v15, s[40:41]
	v_cndmask_b32_e64 v12, v34, v16, s[40:41]
	v_cndmask_b32_e64 v14, v35, v14, s[40:41]
	v_cndmask_b32_e64 v10, v10, v22, s[40:41]
	v_cndmask_b32_e64 v11, v11, v20, s[40:41]
	v_fmac_f32_e32 v0, v17, v13
	v_cndmask_b32_e64 v16, v32, v19, s[40:41]
	v_cndmask_b32_e64 v17, v33, v18, s[40:41]
	v_cvt_pk_bf16_f32 v10, v10, v11
	v_cvt_pk_bf16_f32 v11, v16, v17
	v_cvt_pk_bf16_f32 v12, v12, v14
	v_add_co_u32_e32 v14, vcc, 0xc8ca000, v30
	v_cndmask_b32_e64 v0, v13, v0, s[40:41]
	v_cvt_pk_bf16_f32 v13, v15, v0
	s_nop 0
	v_addc_co_u32_e32 v15, vcc, 0, v31, vcc
	global_store_dwordx4 v[14:15], v[10:13], off offset:1024
	s_branch .LBB0_713
